# C2a pass loop: 15 of 16 per-element LUT lookups hoisted behind the QK MFMAs into free registers (v022 base)
# speedup vs baseline: 1.0022x; 1.0017x over previous
; #define MFMA32(a, b, c) __builtin_amdgcn_mfma_f32_32x32x16_bf16((a), (b), (c), 0, 0, 0)
; DI int crow(int reg, int hh) { return (reg & 3) + 8 * (reg >> 2) + 4 * hh; }
; DI void phaseC2a(const Params& p, float* lut) {
;     ...
;         for (int tile = 0; tile < 4; ++tile) {
;           f32x16 s;
; #pragma unroll
;           for (int e = 0; e < 16; ++e) s[e] = 0.f;
; #pragma unroll
;           for (int ks = 0; ks < 4; ++ks) s = MFMA32(ld16(kcb + tile * 2048 + ks * 512), qf[ks], s);
;           int tt0 = t; asm volatile("" : "+v"(tt0));
; #pragma unroll
;           for (int e = 0; e < 16; ++e) {
;             const int nn = tile * 32 + crow(e, hh);
;             const int dist = tt0 - (16 * nn + 31);
;             const bool ok = dist >= 0 && nn < 127;
;             const int di = dist < 0 ? 0 : (dist > 127 ? 127 : dist);
;             const float lg = __builtin_fmaf(s[e], 0.18033688011112042f, lut[(4 + hd) * 128 + di]);
;             if (pass == 0) mx = fmaxf(mx, ok ? lg : -1e30f);
;             else sum += ok ? __builtin_amdgcn_exp2f(lg - mx) : 0.f;
;           }
;         }
.LBB0_100:
	ds_read_b128 v[2:5], v73
	ds_read_b128 v[76:79], v73 offset:1024
	v_mov_b32_e32 v75, v216
	s_mov_b64 s[2:3], -1
	s_and_b64 vcc, exec, s[8:9]
	s_waitcnt vmcnt(3) lgkmcnt(1)
	v_mfma_f32_32x32x16_bf16 v[2:17], v[2:5], v[30:33], 0
	s_waitcnt vmcnt(2) lgkmcnt(0)
	v_mfma_f32_32x32x16_bf16 v[2:17], v[76:79], v[26:29], v[2:17]
	ds_read_b128 v[76:79], v73 offset:2048
	s_waitcnt vmcnt(1) lgkmcnt(0)
	v_mfma_f32_32x32x16_bf16 v[2:17], v[76:79], v[22:25], v[2:17]
	ds_read_b128 v[76:79], v73 offset:3072
	s_nop 0
	v_add3_u32 v75, v213, v75, s69
	s_waitcnt vmcnt(0) lgkmcnt(0)
	v_mfma_f32_32x32x16_bf16 v[2:17], v[76:79], v[18:21], v[2:17]
	v_subrev_u32_e32 v220, 31, v75
	v_med3_i32 v220, v220, 0, v234
	v_lshl_add_u32 v220, v220, 2, s14
	ds_read_b32 v220, v220 offset:2048
	v_subrev_u32_e32 v221, 47, v75
	v_med3_i32 v221, v221, 0, v234
	v_lshl_add_u32 v221, v221, 2, s14
	ds_read_b32 v221, v221 offset:2048
	v_subrev_u32_e32 v222, 63, v75
	v_med3_i32 v222, v222, 0, v234
	v_lshl_add_u32 v222, v222, 2, s14
	ds_read_b32 v222, v222 offset:2048
	v_add_u32_e32 v223, 0xffffffb1, v75
	v_med3_i32 v223, v223, 0, v234
	v_lshl_add_u32 v223, v223, 2, s14
	ds_read_b32 v223, v223 offset:2048
	v_add_u32_e32 v224, 0xffffff61, v75
	v_med3_i32 v224, v224, 0, v234
	v_lshl_add_u32 v224, v224, 2, s14
	ds_read_b32 v224, v224 offset:2048
	v_add_u32_e32 v225, 0xffffff51, v75
	v_med3_i32 v225, v225, 0, v234
	v_lshl_add_u32 v225, v225, 2, s14
	ds_read_b32 v225, v225 offset:2048
	v_add_u32_e32 v226, 0xffffff41, v75
	v_med3_i32 v226, v226, 0, v234
	v_lshl_add_u32 v226, v226, 2, s14
	ds_read_b32 v226, v226 offset:2048
	v_add_u32_e32 v227, 0xffffff31, v75
	v_med3_i32 v227, v227, 0, v234
	v_lshl_add_u32 v227, v227, 2, s14
	ds_read_b32 v227, v227 offset:2048
	v_add_u32_e32 v228, 0xfffffee1, v75
	v_med3_i32 v228, v228, 0, v234
	v_lshl_add_u32 v228, v228, 2, s14
	ds_read_b32 v228, v228 offset:2048
	v_add_u32_e32 v229, 0xfffffed1, v75
	v_med3_i32 v229, v229, 0, v234
	v_lshl_add_u32 v229, v229, 2, s14
	ds_read_b32 v229, v229 offset:2048
	v_add_u32_e32 v240, 0xfffffec1, v75
	v_med3_i32 v240, v240, 0, v234
	v_lshl_add_u32 v240, v240, 2, s14
	ds_read_b32 v240, v240 offset:2048
	v_add_u32_e32 v241, 0xfffffeb1, v75
	v_med3_i32 v241, v241, 0, v234
	v_lshl_add_u32 v241, v241, 2, s14
	ds_read_b32 v241, v241 offset:2048
	v_add_u32_e32 v242, 0xfffffe61, v75
	v_med3_i32 v242, v242, 0, v234
	v_lshl_add_u32 v242, v242, 2, s14
	ds_read_b32 v242, v242 offset:2048
	v_add_u32_e32 v243, 0xfffffe51, v75
	v_med3_i32 v243, v243, 0, v234
	v_lshl_add_u32 v243, v243, 2, s14
	ds_read_b32 v243, v243 offset:2048
	v_add_u32_e32 v244, 0xfffffe41, v75
	v_med3_i32 v244, v244, 0, v234
	v_lshl_add_u32 v244, v244, 2, s14
	ds_read_b32 v244, v244 offset:2048
	v_subrev_u32_e32 v76, 31, v75
	v_cmp_lt_i32_e64 s[4:5], -1, v76
	s_waitcnt lgkmcnt(0)
	s_nop 5
	v_mov_b32_e32 v76, v220
	v_fmac_f32_e32 v76, 0x3e38aa3b, v2
	s_cbranch_vccz .LBB0_102
	v_sub_f32_e32 v2, v76, v218
	v_exp_f32_e32 v2, v2
	s_mov_b64 s[2:3], 0
	v_cndmask_b32_e64 v2, 0, v2, s[4:5]
	v_add_f32_e32 v2, v72, v2

; DI int crow(int reg, int hh) { return (reg & 3) + 8 * (reg >> 2) + 4 * hh; }
; DI void phaseC2a(const Params& p, float* lut) {
;     ...
;           for (int e = 0; e < 16; ++e) {
;             const int nn = tile * 32 + crow(e, hh);
;             const int dist = tt0 - (16 * nn + 31);
;             const bool ok = dist >= 0 && nn < 127;
;             const int di = dist < 0 ? 0 : (dist > 127 ? 127 : dist);
;             const float lg = __builtin_fmaf(s[e], 0.18033688011112042f, lut[(4 + hd) * 128 + di]);
;             if (pass == 0) mx = fmaxf(mx, ok ? lg : -1e30f);
;             else sum += ok ? __builtin_amdgcn_exp2f(lg - mx) : 0.f;
.LBB0_105:
	v_subrev_u32_e32 v2, 47, v75
	v_cmp_lt_i32_e64 s[6:7], -1, v2
	s_mov_b64 s[2:3], -1
	s_andn2_b64 vcc, exec, s[8:9]
	s_waitcnt lgkmcnt(0)
	v_mov_b32_e32 v2, v221
	v_fmac_f32_e32 v2, 0x3e38aa3b, v3
	v_cndmask_b32_e64 v3, 0, 1, s[8:9]
	v_cmp_ne_u32_e64 s[4:5], 1, v3
	s_cbranch_vccnz .LBB0_107
	v_sub_f32_e32 v3, v2, v218
	v_exp_f32_e32 v3, v3
	s_mov_b64 s[2:3], 0
	v_cndmask_b32_e64 v3, 0, v3, s[6:7]
	v_add_f32_e32 v3, v72, v3

; DI int crow(int reg, int hh) { return (reg & 3) + 8 * (reg >> 2) + 4 * hh; }
; DI void phaseC2a(const Params& p, float* lut) {
;     ...
;           for (int e = 0; e < 16; ++e) {
;             const int nn = tile * 32 + crow(e, hh);
;             const int dist = tt0 - (16 * nn + 31);
;             const bool ok = dist >= 0 && nn < 127;
;             const int di = dist < 0 ? 0 : (dist > 127 ? 127 : dist);
;             const float lg = __builtin_fmaf(s[e], 0.18033688011112042f, lut[(4 + hd) * 128 + di]);
;             if (pass == 0) mx = fmaxf(mx, ok ? lg : -1e30f);
;             else sum += ok ? __builtin_amdgcn_exp2f(lg - mx) : 0.f;
.LBB0_110:
	v_subrev_u32_e32 v2, 63, v75
	v_cmp_lt_i32_e64 s[6:7], -1, v2
	s_mov_b64 s[2:3], -1
	s_and_b64 vcc, exec, s[4:5]
	s_waitcnt lgkmcnt(0)
	v_mov_b32_e32 v2, v222
	v_fmac_f32_e32 v2, 0x3e38aa3b, v4
	s_cbranch_vccnz .LBB0_112
	v_sub_f32_e32 v3, v2, v218
	v_exp_f32_e32 v3, v3
	s_mov_b64 s[2:3], 0
	v_cndmask_b32_e64 v3, 0, v3, s[6:7]
	v_add_f32_e32 v3, v72, v3

; DI int crow(int reg, int hh) { return (reg & 3) + 8 * (reg >> 2) + 4 * hh; }
; DI void phaseC2a(const Params& p, float* lut) {
;     ...
;           for (int e = 0; e < 16; ++e) {
;             const int nn = tile * 32 + crow(e, hh);
;             const int dist = tt0 - (16 * nn + 31);
;             const bool ok = dist >= 0 && nn < 127;
;             const int di = dist < 0 ? 0 : (dist > 127 ? 127 : dist);
;             const float lg = __builtin_fmaf(s[e], 0.18033688011112042f, lut[(4 + hd) * 128 + di]);
;             if (pass == 0) mx = fmaxf(mx, ok ? lg : -1e30f);
;             else sum += ok ? __builtin_amdgcn_exp2f(lg - mx) : 0.f;
.LBB0_115:
	v_add_u32_e32 v2, 0xffffffb1, v75
	v_cmp_lt_i32_e64 s[6:7], -1, v2
	s_mov_b64 s[2:3], -1
	s_and_b64 vcc, exec, s[4:5]
	s_waitcnt lgkmcnt(0)
	v_mov_b32_e32 v2, v223
	v_fmac_f32_e32 v2, 0x3e38aa3b, v5
	s_cbranch_vccnz .LBB0_117
	v_sub_f32_e32 v3, v2, v218
	v_exp_f32_e32 v3, v3
	s_mov_b64 s[2:3], 0
	v_cndmask_b32_e64 v3, 0, v3, s[6:7]
	v_add_f32_e32 v3, v72, v3

; DI int crow(int reg, int hh) { return (reg & 3) + 8 * (reg >> 2) + 4 * hh; }
; DI void phaseC2a(const Params& p, float* lut) {
;     ...
;           for (int e = 0; e < 16; ++e) {
;             const int nn = tile * 32 + crow(e, hh);
;             const int dist = tt0 - (16 * nn + 31);
;             const bool ok = dist >= 0 && nn < 127;
;             const int di = dist < 0 ? 0 : (dist > 127 ? 127 : dist);
;             const float lg = __builtin_fmaf(s[e], 0.18033688011112042f, lut[(4 + hd) * 128 + di]);
;             if (pass == 0) mx = fmaxf(mx, ok ? lg : -1e30f);
;             else sum += ok ? __builtin_amdgcn_exp2f(lg - mx) : 0.f;
.LBB0_120:
	v_add_u32_e32 v2, 0xffffff61, v75
	v_cmp_lt_i32_e64 s[6:7], -1, v2
	s_mov_b64 s[2:3], -1
	s_and_b64 vcc, exec, s[4:5]
	s_waitcnt lgkmcnt(0)
	v_mov_b32_e32 v2, v224
	v_fmac_f32_e32 v2, 0x3e38aa3b, v6
	s_cbranch_vccnz .LBB0_122
	v_sub_f32_e32 v3, v2, v218
	v_exp_f32_e32 v3, v3
	s_mov_b64 s[2:3], 0
	v_cndmask_b32_e64 v3, 0, v3, s[6:7]
	v_add_f32_e32 v3, v72, v3

; DI int crow(int reg, int hh) { return (reg & 3) + 8 * (reg >> 2) + 4 * hh; }
; DI void phaseC2a(const Params& p, float* lut) {
;     ...
;           for (int e = 0; e < 16; ++e) {
;             const int nn = tile * 32 + crow(e, hh);
;             const int dist = tt0 - (16 * nn + 31);
;             const bool ok = dist >= 0 && nn < 127;
;             const int di = dist < 0 ? 0 : (dist > 127 ? 127 : dist);
;             const float lg = __builtin_fmaf(s[e], 0.18033688011112042f, lut[(4 + hd) * 128 + di]);
;             if (pass == 0) mx = fmaxf(mx, ok ? lg : -1e30f);
;             else sum += ok ? __builtin_amdgcn_exp2f(lg - mx) : 0.f;
.LBB0_125:
	v_add_u32_e32 v2, 0xffffff51, v75
	v_cmp_lt_i32_e64 s[6:7], -1, v2
	s_mov_b64 s[2:3], -1
	s_and_b64 vcc, exec, s[4:5]
	s_waitcnt lgkmcnt(0)
	v_mov_b32_e32 v2, v225
	v_fmac_f32_e32 v2, 0x3e38aa3b, v7
	s_cbranch_vccnz .LBB0_127
	v_sub_f32_e32 v3, v2, v218
	v_exp_f32_e32 v3, v3
	s_mov_b64 s[2:3], 0
	v_cndmask_b32_e64 v3, 0, v3, s[6:7]
	v_add_f32_e32 v3, v72, v3

; DI int crow(int reg, int hh) { return (reg & 3) + 8 * (reg >> 2) + 4 * hh; }
; DI void phaseC2a(const Params& p, float* lut) {
;     ...
;           for (int e = 0; e < 16; ++e) {
;             const int nn = tile * 32 + crow(e, hh);
;             const int dist = tt0 - (16 * nn + 31);
;             const bool ok = dist >= 0 && nn < 127;
;             const int di = dist < 0 ? 0 : (dist > 127 ? 127 : dist);
;             const float lg = __builtin_fmaf(s[e], 0.18033688011112042f, lut[(4 + hd) * 128 + di]);
;             if (pass == 0) mx = fmaxf(mx, ok ? lg : -1e30f);
;             else sum += ok ? __builtin_amdgcn_exp2f(lg - mx) : 0.f;
.LBB0_130:
	v_add_u32_e32 v2, 0xffffff41, v75
	v_cmp_lt_i32_e64 s[6:7], -1, v2
	s_mov_b64 s[2:3], -1
	s_and_b64 vcc, exec, s[4:5]
	s_waitcnt lgkmcnt(0)
	v_mov_b32_e32 v2, v226
	v_fmac_f32_e32 v2, 0x3e38aa3b, v8
	s_cbranch_vccnz .LBB0_132
	v_sub_f32_e32 v3, v2, v218
	v_exp_f32_e32 v3, v3
	s_mov_b64 s[2:3], 0
	v_cndmask_b32_e64 v3, 0, v3, s[6:7]
	v_add_f32_e32 v3, v72, v3

; DI int crow(int reg, int hh) { return (reg & 3) + 8 * (reg >> 2) + 4 * hh; }
; DI void phaseC2a(const Params& p, float* lut) {
;     ...
;           for (int e = 0; e < 16; ++e) {
;             const int nn = tile * 32 + crow(e, hh);
;             const int dist = tt0 - (16 * nn + 31);
;             const bool ok = dist >= 0 && nn < 127;
;             const int di = dist < 0 ? 0 : (dist > 127 ? 127 : dist);
;             const float lg = __builtin_fmaf(s[e], 0.18033688011112042f, lut[(4 + hd) * 128 + di]);
;             if (pass == 0) mx = fmaxf(mx, ok ? lg : -1e30f);
;             else sum += ok ? __builtin_amdgcn_exp2f(lg - mx) : 0.f;
.LBB0_135:
	v_add_u32_e32 v2, 0xffffff31, v75
	v_cmp_lt_i32_e64 s[6:7], -1, v2
	s_mov_b64 s[2:3], -1
	s_and_b64 vcc, exec, s[4:5]
	s_waitcnt lgkmcnt(0)
	v_mov_b32_e32 v2, v227
	v_fmac_f32_e32 v2, 0x3e38aa3b, v9
	s_cbranch_vccnz .LBB0_137
	v_sub_f32_e32 v3, v2, v218
	v_exp_f32_e32 v3, v3
	s_mov_b64 s[2:3], 0
	v_cndmask_b32_e64 v3, 0, v3, s[6:7]
	v_add_f32_e32 v3, v72, v3

; DI int crow(int reg, int hh) { return (reg & 3) + 8 * (reg >> 2) + 4 * hh; }
; DI void phaseC2a(const Params& p, float* lut) {
;     ...
;           for (int e = 0; e < 16; ++e) {
;             const int nn = tile * 32 + crow(e, hh);
;             const int dist = tt0 - (16 * nn + 31);
;             const bool ok = dist >= 0 && nn < 127;
;             const int di = dist < 0 ? 0 : (dist > 127 ? 127 : dist);
;             const float lg = __builtin_fmaf(s[e], 0.18033688011112042f, lut[(4 + hd) * 128 + di]);
;             if (pass == 0) mx = fmaxf(mx, ok ? lg : -1e30f);
;             else sum += ok ? __builtin_amdgcn_exp2f(lg - mx) : 0.f;
.LBB0_140:
	v_add_u32_e32 v2, 0xfffffee1, v75
	v_cmp_lt_i32_e64 s[6:7], -1, v2
	s_mov_b64 s[2:3], -1
	s_and_b64 vcc, exec, s[4:5]
	s_waitcnt lgkmcnt(0)
	v_mov_b32_e32 v2, v228
	v_fmac_f32_e32 v2, 0x3e38aa3b, v10
	s_cbranch_vccnz .LBB0_142
	v_sub_f32_e32 v3, v2, v218
	v_exp_f32_e32 v3, v3
	s_mov_b64 s[2:3], 0
	v_cndmask_b32_e64 v3, 0, v3, s[6:7]
	v_add_f32_e32 v3, v72, v3

; DI int crow(int reg, int hh) { return (reg & 3) + 8 * (reg >> 2) + 4 * hh; }
; DI void phaseC2a(const Params& p, float* lut) {
;     ...
;           for (int e = 0; e < 16; ++e) {
;             const int nn = tile * 32 + crow(e, hh);
;             const int dist = tt0 - (16 * nn + 31);
;             const bool ok = dist >= 0 && nn < 127;
;             const int di = dist < 0 ? 0 : (dist > 127 ? 127 : dist);
;             const float lg = __builtin_fmaf(s[e], 0.18033688011112042f, lut[(4 + hd) * 128 + di]);
;             if (pass == 0) mx = fmaxf(mx, ok ? lg : -1e30f);
;             else sum += ok ? __builtin_amdgcn_exp2f(lg - mx) : 0.f;
.LBB0_145:
	v_add_u32_e32 v2, 0xfffffed1, v75
	v_cmp_lt_i32_e64 s[6:7], -1, v2
	s_mov_b64 s[2:3], -1
	s_and_b64 vcc, exec, s[4:5]
	s_waitcnt lgkmcnt(0)
	v_mov_b32_e32 v2, v229
	v_fmac_f32_e32 v2, 0x3e38aa3b, v11
	s_cbranch_vccnz .LBB0_147
	v_sub_f32_e32 v3, v2, v218
	v_exp_f32_e32 v3, v3
	s_mov_b64 s[2:3], 0
	v_cndmask_b32_e64 v3, 0, v3, s[6:7]
	v_add_f32_e32 v3, v72, v3

; DI int crow(int reg, int hh) { return (reg & 3) + 8 * (reg >> 2) + 4 * hh; }
; DI void phaseC2a(const Params& p, float* lut) {
;     ...
;           for (int e = 0; e < 16; ++e) {
;             const int nn = tile * 32 + crow(e, hh);
;             const int dist = tt0 - (16 * nn + 31);
;             const bool ok = dist >= 0 && nn < 127;
;             const int di = dist < 0 ? 0 : (dist > 127 ? 127 : dist);
;             const float lg = __builtin_fmaf(s[e], 0.18033688011112042f, lut[(4 + hd) * 128 + di]);
;             if (pass == 0) mx = fmaxf(mx, ok ? lg : -1e30f);
;             else sum += ok ? __builtin_amdgcn_exp2f(lg - mx) : 0.f;
.LBB0_150:
	v_add_u32_e32 v2, 0xfffffec1, v75
	v_cmp_lt_i32_e64 s[6:7], -1, v2
	s_mov_b64 s[2:3], -1
	s_and_b64 vcc, exec, s[4:5]
	s_waitcnt lgkmcnt(0)
	v_mov_b32_e32 v2, v240
	v_fmac_f32_e32 v2, 0x3e38aa3b, v12
	s_cbranch_vccnz .LBB0_152
	v_sub_f32_e32 v3, v2, v218
	v_exp_f32_e32 v3, v3
	s_mov_b64 s[2:3], 0
	v_cndmask_b32_e64 v3, 0, v3, s[6:7]
	v_add_f32_e32 v3, v72, v3

; DI int crow(int reg, int hh) { return (reg & 3) + 8 * (reg >> 2) + 4 * hh; }
; DI void phaseC2a(const Params& p, float* lut) {
;     ...
;           for (int e = 0; e < 16; ++e) {
;             const int nn = tile * 32 + crow(e, hh);
;             const int dist = tt0 - (16 * nn + 31);
;             const bool ok = dist >= 0 && nn < 127;
;             const int di = dist < 0 ? 0 : (dist > 127 ? 127 : dist);
;             const float lg = __builtin_fmaf(s[e], 0.18033688011112042f, lut[(4 + hd) * 128 + di]);
;             if (pass == 0) mx = fmaxf(mx, ok ? lg : -1e30f);
;             else sum += ok ? __builtin_amdgcn_exp2f(lg - mx) : 0.f;
.LBB0_155:
	v_add_u32_e32 v2, 0xfffffeb1, v75
	v_cmp_lt_i32_e64 s[6:7], -1, v2
	s_mov_b64 s[2:3], -1
	s_and_b64 vcc, exec, s[4:5]
	s_waitcnt lgkmcnt(0)
	v_mov_b32_e32 v2, v241
	v_fmac_f32_e32 v2, 0x3e38aa3b, v13
	s_cbranch_vccnz .LBB0_157
	v_sub_f32_e32 v3, v2, v218
	v_exp_f32_e32 v3, v3
	s_mov_b64 s[2:3], 0
	v_cndmask_b32_e64 v3, 0, v3, s[6:7]
	v_add_f32_e32 v3, v72, v3

; DI int crow(int reg, int hh) { return (reg & 3) + 8 * (reg >> 2) + 4 * hh; }
; DI void phaseC2a(const Params& p, float* lut) {
;     ...
;           for (int e = 0; e < 16; ++e) {
;             const int nn = tile * 32 + crow(e, hh);
;             const int dist = tt0 - (16 * nn + 31);
;             const bool ok = dist >= 0 && nn < 127;
;             const int di = dist < 0 ? 0 : (dist > 127 ? 127 : dist);
;             const float lg = __builtin_fmaf(s[e], 0.18033688011112042f, lut[(4 + hd) * 128 + di]);
;             if (pass == 0) mx = fmaxf(mx, ok ? lg : -1e30f);
;             else sum += ok ? __builtin_amdgcn_exp2f(lg - mx) : 0.f;
.LBB0_160:
	v_add_u32_e32 v2, 0xfffffe61, v75
	v_cmp_lt_i32_e64 s[6:7], -1, v2
	s_mov_b64 s[2:3], -1
	s_and_b64 vcc, exec, s[4:5]
	s_waitcnt lgkmcnt(0)
	v_mov_b32_e32 v2, v242
	v_fmac_f32_e32 v2, 0x3e38aa3b, v14
	s_cbranch_vccnz .LBB0_162
	v_sub_f32_e32 v3, v2, v218
	v_exp_f32_e32 v3, v3
	s_mov_b64 s[2:3], 0
	v_cndmask_b32_e64 v3, 0, v3, s[6:7]
	v_add_f32_e32 v3, v72, v3

; DI int crow(int reg, int hh) { return (reg & 3) + 8 * (reg >> 2) + 4 * hh; }
; DI void phaseC2a(const Params& p, float* lut) {
;     ...
;           for (int e = 0; e < 16; ++e) {
;             const int nn = tile * 32 + crow(e, hh);
;             const int dist = tt0 - (16 * nn + 31);
;             const bool ok = dist >= 0 && nn < 127;
;             const int di = dist < 0 ? 0 : (dist > 127 ? 127 : dist);
;             const float lg = __builtin_fmaf(s[e], 0.18033688011112042f, lut[(4 + hd) * 128 + di]);
;             if (pass == 0) mx = fmaxf(mx, ok ? lg : -1e30f);
;             else sum += ok ? __builtin_amdgcn_exp2f(lg - mx) : 0.f;
.LBB0_165:
	v_add_u32_e32 v2, 0xfffffe51, v75
	v_cmp_lt_i32_e64 s[6:7], -1, v2
	s_mov_b64 s[2:3], -1
	s_and_b64 vcc, exec, s[4:5]
	s_waitcnt lgkmcnt(0)
	v_mov_b32_e32 v2, v243
	v_fmac_f32_e32 v2, 0x3e38aa3b, v15
	s_cbranch_vccnz .LBB0_167
	v_sub_f32_e32 v3, v2, v218
	v_exp_f32_e32 v3, v3
	s_mov_b64 s[2:3], 0
	v_cndmask_b32_e64 v3, 0, v3, s[6:7]
	v_add_f32_e32 v3, v72, v3

; DI int crow(int reg, int hh) { return (reg & 3) + 8 * (reg >> 2) + 4 * hh; }
; DI void phaseC2a(const Params& p, float* lut) {
;     ...
;           for (int e = 0; e < 16; ++e) {
;             const int nn = tile * 32 + crow(e, hh);
;             const int dist = tt0 - (16 * nn + 31);
;             const bool ok = dist >= 0 && nn < 127;
;             const int di = dist < 0 ? 0 : (dist > 127 ? 127 : dist);
;             const float lg = __builtin_fmaf(s[e], 0.18033688011112042f, lut[(4 + hd) * 128 + di]);
;             if (pass == 0) mx = fmaxf(mx, ok ? lg : -1e30f);
;             else sum += ok ? __builtin_amdgcn_exp2f(lg - mx) : 0.f;
.LBB0_170:
	v_add_u32_e32 v2, 0xfffffe41, v75
	v_cmp_lt_i32_e64 s[6:7], -1, v2
	s_mov_b64 s[2:3], -1
	s_and_b64 vcc, exec, s[4:5]
	s_waitcnt lgkmcnt(0)
	v_mov_b32_e32 v2, v244
	v_fmac_f32_e32 v2, 0x3e38aa3b, v16
	s_cbranch_vccnz .LBB0_172
	v_sub_f32_e32 v3, v2, v218
	v_exp_f32_e32 v3, v3
	s_mov_b64 s[2:3], 0
	v_cndmask_b32_e64 v3, 0, v3, s[6:7]
	v_add_f32_e32 v3, v72, v3
